# v8 + attention loop: three of the four K/V tile DMA issues moved into the gaps behind QK^T MFMAs 5-7 (the fourth stays behind MFMA 8 and keeps the 12 states in front of the row maximum)
# speedup vs baseline: 1.0179x; 1.0007x over previous
.LBB0_1309:
	s_waitcnt lgkmcnt(7)
	v_mfma_f32_32x32x16_bf16 v[114:129], v[190:193], v[150:153], v[218:233]
	v_add_f32_e32 v98, v82, v83
	v_add_f32_e32 v98, v84, v98
	v_add_f32_e32 v98, v85, v98
	v_add_f32_e32 v98, v86, v98
	v_add_u32_e32 v247, s30, v246
	v_add_f32_e32 v98, v87, v98
	v_cvt_pk_bf16_f32 v158, v82, v83
	v_cvt_pk_bf16_f32 v159, v84, v85
	s_nop 0
	v_add_f32_e32 v82, v88, v98
	s_waitcnt lgkmcnt(6)
	v_mfma_f32_32x32x16_bf16 v[98:113], v[182:185], v[150:153], v[218:233]
	v_add_f32_e32 v82, v89, v82
	v_add_f32_e32 v82, v90, v82
	v_add_f32_e32 v82, v91, v82
	v_cvt_pk_bf16_f32 v160, v86, v87
	v_cvt_pk_bf16_f32 v161, v88, v89
	s_waitcnt lgkmcnt(5)
	v_mfma_f32_32x32x16_bf16 v[114:129], v[186:189], v[146:149], v[114:129]
	v_add_f32_e32 v82, v92, v82
	v_add_f32_e32 v82, v93, v82
	v_add_f32_e32 v82, v94, v82
	v_add_f32_e32 v82, v95, v82
	v_cvt_pk_bf16_f32 v154, v90, v91
	v_cvt_pk_bf16_f32 v155, v92, v93
	s_waitcnt lgkmcnt(4)
	v_mfma_f32_32x32x16_bf16 v[98:113], v[178:181], v[146:149], v[98:113]
	v_add_f32_e32 v82, v96, v82
	v_add_f32_e32 v82, v97, v82
	v_add_f32_e32 v82, v66, v82
	v_add_f32_e32 v86, v67, v82
	v_cvt_pk_bf16_f32 v156, v94, v95
	v_cvt_pk_bf16_f32 v157, v96, v97
	ds_read_b64_tr_b16 v[82:83], v247 offset:49152
	ds_read_b64_tr_b16 v[84:85], v247 offset:49664
	s_waitcnt lgkmcnt(5)
	v_mfma_f32_32x32x16_bf16 v[114:129], v[174:177], v[142:145], v[114:129]
	v_add_f32_e32 v86, v68, v86
	v_add_f32_e32 v86, v69, v86
	v_add_f32_e32 v86, v70, v86
	v_add_f32_e32 v86, v71, v86
	v_cvt_pk_bf16_f32 v138, v66, v67
	v_cvt_pk_bf16_f32 v139, v68, v69
	ds_read_b64_tr_b16 v[66:67], v247 offset:50176
	ds_read_b64_tr_b16 v[68:69], v247 offset:50688
	v_lshl_add_u64 v[188:189], v[214:215], 0, s[52:53]
	v_lshl_add_u64 v[92:93], v[188:189], 0, s[70:71]
	s_add_i32 s27, s91, s25
	s_mov_b32 s30, m0
	s_mov_b32 m0, s27
	s_nop 0
	global_load_lds_dwordx4 v[92:93], off
	s_mov_b32 m0, s30
	s_waitcnt lgkmcnt(6)
	v_mfma_f32_32x32x16_bf16 v[98:113], v[170:173], v[142:145], v[98:113]
	v_add_f32_e32 v86, v72, v86
	v_add_f32_e32 v86, v73, v86
	v_add_f32_e32 v86, v74, v86
	v_add_f32_e32 v86, v75, v86
	v_cvt_pk_bf16_f32 v140, v70, v71
	v_cvt_pk_bf16_f32 v141, v72, v73
	ds_read_b64_tr_b16 v[70:71], v247 offset:53248
	ds_read_b64_tr_b16 v[72:73], v247 offset:53760
	v_lshl_add_u64 v[92:93], v[188:189], 0, s[72:73]
	v_lshl_add_u64 v[186:187], v[216:217], 0, s[52:53]
	s_addk_i32 s27, 0x2000
	s_mov_b32 s30, m0
	s_mov_b32 m0, s27
	s_nop 0
	global_load_lds_dwordx4 v[92:93], off
	s_mov_b32 m0, s30
	s_waitcnt lgkmcnt(7)
	v_mfma_f32_32x32x16_bf16 v[114:129], v[166:169], v[134:137], v[114:129]
	v_add_f32_e32 v86, v76, v86
	v_add_f32_e32 v86, v77, v86
	v_add_f32_e32 v86, v78, v86
	v_add_f32_e32 v86, v79, v86
	v_cvt_pk_bf16_f32 v130, v74, v75
	v_cvt_pk_bf16_f32 v131, v76, v77
	ds_read_b64_tr_b16 v[74:75], v247 offset:54272
	ds_read_b64_tr_b16 v[76:77], v247 offset:54784
	v_lshl_add_u64 v[92:93], v[186:187], 0, s[74:75]
	s_add_i32 s27, s29, s24
	s_mov_b32 s30, m0
	s_mov_b32 m0, s27
	s_nop 0
	global_load_lds_dwordx4 v[92:93], off
	s_mov_b32 m0, s30
	s_waitcnt lgkmcnt(8)
	v_mfma_f32_32x32x16_bf16 v[98:113], v[162:165], v[134:137], v[98:113]
	v_add_f32_e32 v86, v80, v86
	v_add_f32_e32 v86, v81, v86
	v_add_f32_e32 v86, 0, v86
	v_cvt_pk_bf16_f32 v132, v78, v79
	v_cvt_pk_bf16_f32 v133, v80, v81
	v_lshl_add_u64 v[92:93], v[186:187], 0, s[76:77]
	s_addk_i32 s27, 0x2000
	s_mov_b32 s30, m0
	s_mov_b32 m0, s27
	s_nop 0
	global_load_lds_dwordx4 v[92:93], off
	s_mov_b32 m0, s30
	v_max_f32_e32 v78, v115, v115
	v_max_f32_e32 v79, v114, v114
	v_max_f32_e32 v78, v79, v78
	v_max3_f32 v79, v116, v117, v99
	v_max3_f32 v78, v78, v98, v100
	v_max3_f32 v78, v78, v101, v118
	v_max3_f32 v79, v79, v120, v121
	v_max3_f32 v78, v78, v119, v102
	v_max3_f32 v79, v79, v104, v105
	v_max3_f32 v78, v78, v103, v122
	v_max3_f32 v79, v79, v124, v125
	v_max3_f32 v78, v78, v123, v106
	v_max3_f32 v79, v79, v108, v109
	v_max3_f32 v78, v78, v107, v126
	v_max3_f32 v79, v79, v128, v129
	v_max3_f32 v78, v78, v127, v110
	v_max3_f32 v79, v79, v112, v113
	v_max3_f32 v78, v78, v111, v79
	v_mov_b32_e32 v79, v78
	s_nop 1
	v_permlane32_swap_b32_e32 v78, v79
	v_max_f32_e32 v79, v79, v79
	v_max_f32_e32 v78, v78, v78
	v_max_f32_e32 v78, v78, v79
	v_cmp_lt_f32_e32 vcc, s93, v78
	s_cmp_lg_u64 vcc, 0
	v_add_f32_e32 v190, v250, v86
	s_cselect_b64 s[36:37], -1, 0
	s_cbranch_vccnz .LBB0_1317

.LBB0_1312:
	s_add_i32 s27, s29, 0x4000
	s_cmpk_lg_u32 s29, 0x8000
	s_cselect_b32 s27, s27, 0
	v_mfma_f32_32x32x16_bf16 v[82:97], v[70:73], v[150:153], v[218:233]
	v_add_f32_e32 v74, v114, v115
	v_add_f32_e32 v74, v116, v74
	v_add_f32_e32 v74, v117, v74
	v_add_f32_e32 v74, v118, v74
	v_add_u32_e32 v247, s91, v246
	v_add_f32_e32 v74, v119, v74
	v_cvt_pk_bf16_f32 v158, v114, v115
	v_cvt_pk_bf16_f32 v159, v116, v117
	s_nop 0
	v_add_f32_e32 v70, v120, v74
	v_add_f32_e32 v70, v121, v70
	v_add_f32_e32 v70, v122, v70
	v_add_f32_e32 v114, v123, v70
	v_mfma_f32_32x32x16_bf16 v[66:81], v[66:69], v[150:153], v[218:233]
	v_cvt_pk_bf16_f32 v160, v118, v119
	v_cvt_pk_bf16_f32 v161, v120, v121
	v_mfma_f32_32x32x16_bf16 v[82:97], v[182:185], v[146:149], v[82:97]
	v_add_f32_e32 v114, v124, v114
	v_add_f32_e32 v114, v125, v114
	v_add_f32_e32 v114, v126, v114
	v_add_f32_e32 v114, v127, v114
	v_cvt_pk_bf16_f32 v154, v122, v123
	v_cvt_pk_bf16_f32 v155, v124, v125
	v_mfma_f32_32x32x16_bf16 v[66:81], v[174:177], v[146:149], v[66:81]
	v_add_f32_e32 v114, v128, v114
	v_add_f32_e32 v114, v129, v114
	v_add_f32_e32 v114, v98, v114
	v_add_f32_e32 v118, v99, v114
	v_cvt_pk_bf16_f32 v156, v126, v127
	v_cvt_pk_bf16_f32 v157, v128, v129
	ds_read_b64_tr_b16 v[114:115], v247 offset:49152
	ds_read_b64_tr_b16 v[116:117], v247 offset:49664
	v_mfma_f32_32x32x16_bf16 v[82:97], v[178:181], v[142:145], v[82:97]
	v_add_f32_e32 v118, v100, v118
	v_add_f32_e32 v118, v101, v118
	v_add_f32_e32 v118, v102, v118
	v_add_f32_e32 v118, v103, v118
	v_cvt_pk_bf16_f32 v138, v98, v99
	v_cvt_pk_bf16_f32 v139, v100, v101
	ds_read_b64_tr_b16 v[98:99], v247 offset:50176
	ds_read_b64_tr_b16 v[100:101], v247 offset:50688
	s_mov_b64 s[30:31], 0x1dd40000
	v_lshl_add_u64 v[124:125], v[188:189], 0, s[30:31]
	s_add_i32 s36, s29, s25
	s_mov_b32 s30, m0
	s_mov_b32 m0, s36
	s_nop 0
	global_load_lds_dwordx4 v[124:125], off
	s_mov_b32 m0, s30
	v_mfma_f32_32x32x16_bf16 v[66:81], v[166:169], v[142:145], v[66:81]
	v_add_f32_e32 v118, v104, v118
	v_add_f32_e32 v118, v105, v118
	v_add_f32_e32 v118, v106, v118
	v_add_f32_e32 v118, v107, v118
	v_cvt_pk_bf16_f32 v140, v102, v103
	v_cvt_pk_bf16_f32 v141, v104, v105
	ds_read_b64_tr_b16 v[102:103], v247 offset:53248
	ds_read_b64_tr_b16 v[104:105], v247 offset:53760
	s_mov_b64 s[30:31], 0x1dd40080
	v_lshl_add_u64 v[124:125], v[188:189], 0, s[30:31]
	s_add_i32 s30, s36, 0x2000
	s_mov_b32 s31, m0
	s_mov_b32 m0, s30
	s_nop 0
	global_load_lds_dwordx4 v[124:125], off
	s_mov_b32 m0, s31
	v_mfma_f32_32x32x16_bf16 v[82:97], v[170:173], v[134:137], v[82:97]
	v_add_f32_e32 v118, v108, v118
	v_add_f32_e32 v118, v109, v118
	v_add_f32_e32 v118, v110, v118
	v_add_f32_e32 v118, v111, v118
	v_cvt_pk_bf16_f32 v130, v106, v107
	v_cvt_pk_bf16_f32 v131, v108, v109
	ds_read_b64_tr_b16 v[106:107], v247 offset:54272
	ds_read_b64_tr_b16 v[108:109], v247 offset:54784
	s_mov_b64 s[30:31], 0x25cc0000
	v_lshl_add_u64 v[124:125], v[186:187], 0, s[30:31]
	s_add_i32 s36, s27, s24
	s_mov_b32 s30, m0
	s_mov_b32 m0, s36
	s_nop 0
	global_load_lds_dwordx4 v[124:125], off
	s_mov_b32 m0, s30
	v_mfma_f32_32x32x16_bf16 v[66:81], v[162:165], v[134:137], v[66:81]
	v_add_f32_e32 v118, v112, v118
	v_add_f32_e32 v118, v113, v118
	v_add_f32_e32 v118, 0, v118
	v_cvt_pk_bf16_f32 v132, v110, v111
	v_cvt_pk_bf16_f32 v133, v112, v113
	s_mov_b64 s[30:31], 0x25cc0080
	v_lshl_add_u64 v[124:125], v[186:187], 0, s[30:31]
	s_add_i32 s30, s36, 0x2000
	s_mov_b32 s31, m0
	s_mov_b32 m0, s30
	s_nop 0
	global_load_lds_dwordx4 v[124:125], off
	s_mov_b32 m0, s31
	v_max_f32_e32 v110, v83, v83
	v_max_f32_e32 v111, v82, v82
	v_max_f32_e32 v110, v111, v110
	v_max3_f32 v111, v84, v85, v67
	v_max3_f32 v110, v110, v66, v68
	v_max3_f32 v110, v110, v69, v86
	v_max3_f32 v111, v111, v88, v89
	v_max3_f32 v110, v110, v87, v70
	v_max3_f32 v111, v111, v72, v73
	v_max3_f32 v110, v110, v71, v90
	v_max3_f32 v111, v111, v92, v93
	v_max3_f32 v110, v110, v91, v74
	v_max3_f32 v111, v111, v76, v77
	v_max3_f32 v110, v110, v75, v94
	v_max3_f32 v111, v111, v96, v97
	v_max3_f32 v110, v110, v95, v78
	v_max3_f32 v111, v111, v80, v81
	v_max3_f32 v110, v110, v79, v111
	v_mov_b32_e32 v111, v110
	s_nop 1
	v_permlane32_swap_b32_e32 v110, v111
	v_max_f32_e32 v111, v111, v111
	v_max_f32_e32 v110, v110, v110
	v_max_f32_e32 v110, v110, v111
	v_cmp_lt_f32_e32 vcc, s93, v110
	s_cmp_lg_u64 vcc, 0
	v_add_f32_e32 v250, v190, v118
	s_cselect_b64 s[36:37], -1, 0
	s_cbranch_vccnz .LBB0_1320
